# plus adaLN modulation GEMV (prep): 16 strided weight loads in flight per wait instead of 1
# speedup vs baseline: 1.0666x; 1.0091x over previous
.LBB0_1373:
	v_and_b32_e32 v0, 0x3ff, v7
	v_lshlrev_b32_e32 v0, 2, v0
	v_lshl_add_u64 v[8:9], s[46:47], 0, v[0:1]
	v_cmp_gt_u32_e32 vcc, s25, v7
	s_movk_i32 s7, 0x22ff
	s_nop 0
	v_cndmask_b32_e32 v9, v9, v3, vcc
	v_cndmask_b32_e32 v8, v8, v2, vcc
	global_load_dword v0, v[8:9], off
	v_add_u32_e32 v8, 0x100, v7
	v_cmp_lt_u32_e32 vcc, s7, v7
	v_mov_b32_e32 v7, v8
	s_or_b64 s[4:5], vcc, s[4:5]
	v_lshl_add_u64 v[2:3], v[2:3], 0, s[36:37]
	s_waitcnt vmcnt(0)
	v_mul_f32_e32 v8, 0xbfb8aa3b, v0
	v_exp_f32_e32 v8, v8
	s_nop 0
	v_add_f32_e32 v8, 1.0, v8
	v_div_scale_f32 v9, s[8:9], v8, v8, v0
	v_rcp_f32_e32 v10, v9
	v_div_scale_f32 v11, vcc, v0, v8, v0
	s_waitcnt lgkmcnt(0)
	v_fma_f32 v12, -v9, v10, 1.0
	v_fmac_f32_e32 v10, v12, v10
	v_mul_f32_e32 v12, v11, v10
	v_fma_f32 v13, -v9, v12, v11
	v_fmac_f32_e32 v12, v13, v10
	v_fma_f32 v9, -v9, v12, v11
	v_div_fmas_f32 v9, v9, v10, v12
	v_div_fixup_f32 v0, v9, v8, v0
	ds_write_b32 v6, v0
	v_add_u32_e32 v6, 0x400, v6
	s_andn2_b64 exec, exec, s[4:5]
	s_cbranch_execnz .LBB0_1373
	s_or_b64 exec, exec, s[4:5]
	s_mov_b32 s4, 0x2aaaaaab
	v_mul_hi_i32 v0, v4, s4
	v_lshrrev_b32_e32 v2, 31, v0
	v_ashrrev_i32_e32 v0, 4, v0
	v_add_u32_e32 v21, v0, v2
	s_movk_i32 s4, 0x60
	v_mul_lo_u32 v0, v21, s4
	v_sub_u32_e32 v2, v4, v0
	v_and_b32_e32 v35, 63, v5
	v_lshl_or_b32 v24, v2, 6, v35
	v_lshrrev_b32_e32 v2, 6, v18
	v_ashrrev_i32_e32 v25, 31, v24
	v_mul_hi_u32_u24_e32 v3, 0x600000, v2
	v_mul_u32_u24_e32 v2, 0x600000, v2
	s_mov_b32 s4, 0x1800000
	v_mad_i64_i32 v[2:3], s[4:5], v21, s4, v[2:3]
	v_lshlrev_b64 v[22:23], 2, v[24:25]
	v_lshrrev_b32_e32 v0, 6, v18
	v_lshl_add_u64 v[2:3], v[2:3], 0, v[22:23]
	v_mov_b32_e32 v10, 0
	v_lshl_add_u64 v[26:27], s[48:49], 0, v[2:3]
	v_lshl_add_u32 v25, v0, 10, v222
	s_mov_b64 s[4:5], 0
	v_mov_b32_e32 v11, v10
	v_mov_b32_e32 v32, v10
	v_mov_b32_e32 v33, v10
	v_mov_b32_e32 v30, v10
	v_mov_b32_e32 v31, v10
	v_mov_b32_e32 v28, v10
	v_mov_b32_e32 v29, v10
	v_mov_b32_e32 v36, v10
	s_movk_i32 s8, 0x6000
	s_waitcnt lgkmcnt(0)
	s_barrier
	v_mov_b64_e32 v[58:59], v[26:27]
	s_mov_b32 s4, 0x6000
	s_mov_b32 s5, 0
	s_mov_b32 s7, 0
.LBB0_1375:
	global_load_dword v60, v[58:59], off nt
	v_lshl_add_u64 v[58:59], v[58:59], 0, s[4:5]
	global_load_dword v61, v[58:59], off nt
	v_lshl_add_u64 v[58:59], v[58:59], 0, s[4:5]
	global_load_dword v62, v[58:59], off nt
	v_lshl_add_u64 v[58:59], v[58:59], 0, s[4:5]
	global_load_dword v63, v[58:59], off nt
	v_lshl_add_u64 v[58:59], v[58:59], 0, s[4:5]
	global_load_dword v64, v[58:59], off nt
	v_lshl_add_u64 v[58:59], v[58:59], 0, s[4:5]
	global_load_dword v65, v[58:59], off nt
	v_lshl_add_u64 v[58:59], v[58:59], 0, s[4:5]
	global_load_dword v66, v[58:59], off nt
	v_lshl_add_u64 v[58:59], v[58:59], 0, s[4:5]
	global_load_dword v67, v[58:59], off nt
	v_lshl_add_u64 v[58:59], v[58:59], 0, s[4:5]
	global_load_dword v68, v[58:59], off nt
	v_lshl_add_u64 v[58:59], v[58:59], 0, s[4:5]
	global_load_dword v69, v[58:59], off nt
	v_lshl_add_u64 v[58:59], v[58:59], 0, s[4:5]
	global_load_dword v70, v[58:59], off nt
	v_lshl_add_u64 v[58:59], v[58:59], 0, s[4:5]
	global_load_dword v71, v[58:59], off nt
	v_lshl_add_u64 v[58:59], v[58:59], 0, s[4:5]
	global_load_dword v72, v[58:59], off nt
	v_lshl_add_u64 v[58:59], v[58:59], 0, s[4:5]
	global_load_dword v73, v[58:59], off nt
	v_lshl_add_u64 v[58:59], v[58:59], 0, s[4:5]
	global_load_dword v74, v[58:59], off nt
	v_lshl_add_u64 v[58:59], v[58:59], 0, s[4:5]
	global_load_dword v75, v[58:59], off nt
	v_lshl_add_u64 v[58:59], v[58:59], 0, s[4:5]
	ds_read_b128 v[76:79], v25
	ds_read_b128 v[80:83], v25 offset:4096
	ds_read_b128 v[84:87], v25 offset:8192
	ds_read_b128 v[88:91], v25 offset:12288
	ds_read_b128 v[92:95], v25 offset:16384
	ds_read_b128 v[96:99], v25 offset:20480
	ds_read_b128 v[100:103], v25 offset:24576
	ds_read_b128 v[104:107], v25 offset:28672
	ds_read_b128 v[108:111], v25 offset:32768
	s_waitcnt lgkmcnt(0)
	s_waitcnt vmcnt(15)
	v_fmac_f32_e32 v10, v60, v76
	v_fmac_f32_e32 v11, v60, v80
	v_fmac_f32_e32 v32, v60, v84
	v_fmac_f32_e32 v33, v60, v88
	v_fmac_f32_e32 v30, v60, v92
	v_fmac_f32_e32 v31, v60, v96
	v_fmac_f32_e32 v28, v60, v100
	v_fmac_f32_e32 v29, v60, v104
	v_fmac_f32_e32 v36, v60, v108
	s_waitcnt vmcnt(14)
	v_fmac_f32_e32 v10, v61, v77
	v_fmac_f32_e32 v11, v61, v81
	v_fmac_f32_e32 v32, v61, v85
	v_fmac_f32_e32 v33, v61, v89
	v_fmac_f32_e32 v30, v61, v93
	v_fmac_f32_e32 v31, v61, v97
	v_fmac_f32_e32 v28, v61, v101
	v_fmac_f32_e32 v29, v61, v105
	v_fmac_f32_e32 v36, v61, v109
	s_waitcnt vmcnt(13)
	v_fmac_f32_e32 v10, v62, v78
	v_fmac_f32_e32 v11, v62, v82
	v_fmac_f32_e32 v32, v62, v86
	v_fmac_f32_e32 v33, v62, v90
	v_fmac_f32_e32 v30, v62, v94
	v_fmac_f32_e32 v31, v62, v98
	v_fmac_f32_e32 v28, v62, v102
	v_fmac_f32_e32 v29, v62, v106
	v_fmac_f32_e32 v36, v62, v110
	s_waitcnt vmcnt(12)
	v_fmac_f32_e32 v10, v63, v79
	v_fmac_f32_e32 v11, v63, v83
	v_fmac_f32_e32 v32, v63, v87
	v_fmac_f32_e32 v33, v63, v91
	v_fmac_f32_e32 v30, v63, v95
	v_fmac_f32_e32 v31, v63, v99
	v_fmac_f32_e32 v28, v63, v103
	v_fmac_f32_e32 v29, v63, v107
	v_fmac_f32_e32 v36, v63, v111
	ds_read_b128 v[76:79], v25 offset:16
	ds_read_b128 v[80:83], v25 offset:4112
	ds_read_b128 v[84:87], v25 offset:8208
	ds_read_b128 v[88:91], v25 offset:12304
	ds_read_b128 v[92:95], v25 offset:16400
	ds_read_b128 v[96:99], v25 offset:20496
	ds_read_b128 v[100:103], v25 offset:24592
	ds_read_b128 v[104:107], v25 offset:28688
	ds_read_b128 v[108:111], v25 offset:32784
	s_waitcnt lgkmcnt(0)
	s_waitcnt vmcnt(11)
	v_fmac_f32_e32 v10, v64, v76
	v_fmac_f32_e32 v11, v64, v80
	v_fmac_f32_e32 v32, v64, v84
	v_fmac_f32_e32 v33, v64, v88
	v_fmac_f32_e32 v30, v64, v92
	v_fmac_f32_e32 v31, v64, v96
	v_fmac_f32_e32 v28, v64, v100
	v_fmac_f32_e32 v29, v64, v104
	v_fmac_f32_e32 v36, v64, v108
	s_waitcnt vmcnt(10)
	v_fmac_f32_e32 v10, v65, v77
	v_fmac_f32_e32 v11, v65, v81
	v_fmac_f32_e32 v32, v65, v85
	v_fmac_f32_e32 v33, v65, v89
	v_fmac_f32_e32 v30, v65, v93
	v_fmac_f32_e32 v31, v65, v97
	v_fmac_f32_e32 v28, v65, v101
	v_fmac_f32_e32 v29, v65, v105
	v_fmac_f32_e32 v36, v65, v109
	s_waitcnt vmcnt(9)
	v_fmac_f32_e32 v10, v66, v78
	v_fmac_f32_e32 v11, v66, v82
	v_fmac_f32_e32 v32, v66, v86
	v_fmac_f32_e32 v33, v66, v90
	v_fmac_f32_e32 v30, v66, v94
	v_fmac_f32_e32 v31, v66, v98
	v_fmac_f32_e32 v28, v66, v102
	v_fmac_f32_e32 v29, v66, v106
	v_fmac_f32_e32 v36, v66, v110
	s_waitcnt vmcnt(8)
	v_fmac_f32_e32 v10, v67, v79
	v_fmac_f32_e32 v11, v67, v83
	v_fmac_f32_e32 v32, v67, v87
	v_fmac_f32_e32 v33, v67, v91
	v_fmac_f32_e32 v30, v67, v95
	v_fmac_f32_e32 v31, v67, v99
	v_fmac_f32_e32 v28, v67, v103
	v_fmac_f32_e32 v29, v67, v107
	v_fmac_f32_e32 v36, v67, v111
	ds_read_b128 v[76:79], v25 offset:32
	ds_read_b128 v[80:83], v25 offset:4128
	ds_read_b128 v[84:87], v25 offset:8224
	ds_read_b128 v[88:91], v25 offset:12320
	ds_read_b128 v[92:95], v25 offset:16416
	ds_read_b128 v[96:99], v25 offset:20512
	ds_read_b128 v[100:103], v25 offset:24608
	ds_read_b128 v[104:107], v25 offset:28704
	ds_read_b128 v[108:111], v25 offset:32800
	s_waitcnt lgkmcnt(0)
	s_waitcnt vmcnt(7)
	v_fmac_f32_e32 v10, v68, v76
	v_fmac_f32_e32 v11, v68, v80
	v_fmac_f32_e32 v32, v68, v84
	v_fmac_f32_e32 v33, v68, v88
	v_fmac_f32_e32 v30, v68, v92
	v_fmac_f32_e32 v31, v68, v96
	v_fmac_f32_e32 v28, v68, v100
	v_fmac_f32_e32 v29, v68, v104
	v_fmac_f32_e32 v36, v68, v108
	s_waitcnt vmcnt(6)
	v_fmac_f32_e32 v10, v69, v77
	v_fmac_f32_e32 v11, v69, v81
	v_fmac_f32_e32 v32, v69, v85
	v_fmac_f32_e32 v33, v69, v89
	v_fmac_f32_e32 v30, v69, v93
	v_fmac_f32_e32 v31, v69, v97
	v_fmac_f32_e32 v28, v69, v101
	v_fmac_f32_e32 v29, v69, v105
	v_fmac_f32_e32 v36, v69, v109
	s_waitcnt vmcnt(5)
	v_fmac_f32_e32 v10, v70, v78
	v_fmac_f32_e32 v11, v70, v82
	v_fmac_f32_e32 v32, v70, v86
	v_fmac_f32_e32 v33, v70, v90
	v_fmac_f32_e32 v30, v70, v94
	v_fmac_f32_e32 v31, v70, v98
	v_fmac_f32_e32 v28, v70, v102
	v_fmac_f32_e32 v29, v70, v106
	v_fmac_f32_e32 v36, v70, v110
	s_waitcnt vmcnt(4)
	v_fmac_f32_e32 v10, v71, v79
	v_fmac_f32_e32 v11, v71, v83
	v_fmac_f32_e32 v32, v71, v87
	v_fmac_f32_e32 v33, v71, v91
	v_fmac_f32_e32 v30, v71, v95
	v_fmac_f32_e32 v31, v71, v99
	v_fmac_f32_e32 v28, v71, v103
	v_fmac_f32_e32 v29, v71, v107
	v_fmac_f32_e32 v36, v71, v111
	ds_read_b128 v[76:79], v25 offset:48
	ds_read_b128 v[80:83], v25 offset:4144
	ds_read_b128 v[84:87], v25 offset:8240
	ds_read_b128 v[88:91], v25 offset:12336
	ds_read_b128 v[92:95], v25 offset:16432
	ds_read_b128 v[96:99], v25 offset:20528
	ds_read_b128 v[100:103], v25 offset:24624
	ds_read_b128 v[104:107], v25 offset:28720
	ds_read_b128 v[108:111], v25 offset:32816
	s_waitcnt lgkmcnt(0)
	s_waitcnt vmcnt(3)
	v_fmac_f32_e32 v10, v72, v76
	v_fmac_f32_e32 v11, v72, v80
	v_fmac_f32_e32 v32, v72, v84
	v_fmac_f32_e32 v33, v72, v88
	v_fmac_f32_e32 v30, v72, v92
	v_fmac_f32_e32 v31, v72, v96
	v_fmac_f32_e32 v28, v72, v100
	v_fmac_f32_e32 v29, v72, v104
	v_fmac_f32_e32 v36, v72, v108
	s_waitcnt vmcnt(2)
	v_fmac_f32_e32 v10, v73, v77
	v_fmac_f32_e32 v11, v73, v81
	v_fmac_f32_e32 v32, v73, v85
	v_fmac_f32_e32 v33, v73, v89
	v_fmac_f32_e32 v30, v73, v93
	v_fmac_f32_e32 v31, v73, v97
	v_fmac_f32_e32 v28, v73, v101
	v_fmac_f32_e32 v29, v73, v105
	v_fmac_f32_e32 v36, v73, v109
	s_waitcnt vmcnt(1)
	v_fmac_f32_e32 v10, v74, v78
	v_fmac_f32_e32 v11, v74, v82
	v_fmac_f32_e32 v32, v74, v86
	v_fmac_f32_e32 v33, v74, v90
	v_fmac_f32_e32 v30, v74, v94
	v_fmac_f32_e32 v31, v74, v98
	v_fmac_f32_e32 v28, v74, v102
	v_fmac_f32_e32 v29, v74, v106
	v_fmac_f32_e32 v36, v74, v110
	s_waitcnt vmcnt(0)
	v_fmac_f32_e32 v10, v75, v79
	v_fmac_f32_e32 v11, v75, v83
	v_fmac_f32_e32 v32, v75, v87
	v_fmac_f32_e32 v33, v75, v91
	v_fmac_f32_e32 v30, v75, v95
	v_fmac_f32_e32 v31, v75, v99
	v_fmac_f32_e32 v28, v75, v103
	v_fmac_f32_e32 v29, v75, v107
	v_fmac_f32_e32 v36, v75, v111
	v_add_u32_e32 v25, 64, v25
	s_add_i32 s7, s7, 1
	s_cmp_eq_u32 s7, 16
	s_cbranch_scc0 .LBB0_1375
	v_mul_u32_u24_e32 v2, 0x900, v0
	v_lshlrev_b32_e32 v4, 2, v35
	v_add3_u32 v2, v222, v2, v4
	ds_write2st64_b32 v2, v10, v11 offset0:144 offset1:145
	ds_write2st64_b32 v2, v32, v33 offset0:146 offset1:147
	ds_write2st64_b32 v2, v30, v31 offset0:148 offset1:149
	ds_write2st64_b32 v2, v28, v29 offset0:150 offset1:151
	ds_write_b32 v2, v36 offset:38912
	v_mad_u64_u32 v[2:3], s[4:5], v21, s13, v[24:25]
	v_readlane_b32 s40, v253, 45
	v_ashrrev_i32_e32 v3, 31, v2
	v_readlane_b32 s41, v253, 46
	v_readlane_b32 s42, v253, 47
	v_readlane_b32 s43, v253, 48
	v_readlane_b32 s44, v253, 49
	v_readlane_b32 s45, v253, 50
	v_readlane_b32 s46, v253, 51
	v_readlane_b32 s47, v253, 52
	v_readlane_b32 s48, v253, 53
	v_readlane_b32 s49, v253, 54
	v_readlane_b32 s50, v253, 55
	v_readlane_b32 s51, v253, 56
	v_readlane_b32 s52, v253, 57
	v_readlane_b32 s53, v253, 58
	v_readlane_b32 s54, v253, 59
	v_readlane_b32 s55, v253, 60
	v_lshl_or_b32 v4, v0, 8, v4
	v_lshl_add_u64 v[2:3], v[2:3], 2, s[50:51]
	v_add_u32_e32 v8, v34, v4
	v_mad_u64_u32 v[4:5], s[4:5], v21, 9, v[0:1]
	v_readlane_b32 s40, v254, 55
	v_mad_i64_i32 v[4:5], s[4:5], v4, s8, v[22:23]
	v_readlane_b32 s48, v254, 63
	v_readlane_b32 s49, v255, 0
	v_add_u32_e32 v6, v19, v20
	v_or_b32_e32 v7, 0xffffff00, v18
	v_lshl_add_u64 v[4:5], s[48:49], 0, v[4:5]
	s_mov_b64 s[4:5], 0
	s_waitcnt lgkmcnt(0)
	s_barrier
	v_readlane_b32 s41, v254, 56
	v_readlane_b32 s42, v254, 57
	v_readlane_b32 s43, v254, 58
	v_readlane_b32 s44, v254, 59
	v_readlane_b32 s45, v254, 60
	v_readlane_b32 s46, v254, 61
	v_readlane_b32 s47, v254, 62
	v_readlane_b32 s50, v255, 1
	v_readlane_b32 s51, v255, 2
	v_readlane_b32 s52, v255, 3
	v_readlane_b32 s53, v255, 4
	v_readlane_b32 s54, v255, 5
	v_readlane_b32 s55, v255, 6
